# A-loop: map-1 K fragment ds_reads hoisted to loop top into spare VGPRs (v230-245), MFMA-to-VALU pad restored to 12 states
# speedup vs baseline: 1.0293x; 1.0056x over previous
; DI float ex2(float x) { return __builtin_amdgcn_exp2f(x); }
; DI f32x16 mfma(bf16x8 a, bf16x8 b, f32x16 c) { return __builtin_amdgcn_mfma_f32_32x32x16_bf16(a, b, c, 0, 0, 0); }
; DI f32x4 mfma16(bf16x8 a, bf16x8 b, f32x4 c) { return __builtin_amdgcn_mfma_f32_16x16x32_bf16(a, b, c, 0, 0, 0); }
; DI void pv_frag_step(f32x16& s0, f32x16& s1, const u16* Vs, f32x16& o0, f32x16& o1, f32x4& ls, bf16x8 ones, int rs, const int (&lo)[4]) {
; #pragma unroll
;   for (int i = 0; i < 16; ++i) { s0[i] = ex2(s0[i]); s1[i] = ex2(s1[i]); }
; #pragma unroll
;   for (int kk = 0; kk < 4; ++kk) {
;     const int s = kk & 1;
;     unsigned u0, u1, u2, u3;
;     if (kk < 2) {
;       u0 = pk2(s0[8 * s], s0[8 * s + 1]); u1 = pk2(s0[8 * s + 2], s0[8 * s + 3]);
;       u2 = pk2(s0[8 * s + 4], s0[8 * s + 5]); u3 = pk2(s0[8 * s + 6], s0[8 * s + 7]);
;     } else {
;       u0 = pk2(s1[8 * s], s1[8 * s + 1]); u1 = pk2(s1[8 * s + 2], s1[8 * s + 3]);
;       u2 = pk2(s1[8 * s + 4], s1[8 * s + 5]); u3 = pk2(s1[8 * s + 6], s1[8 * s + 7]);
;     }
;     u32x4 uu = {u0, u1, u2, u3};
;     bf16x8 pf = __builtin_bit_cast(bf16x8, uu);
;     bf16x8 v0 = ldsv(Vs + lo[kk]);
;     bf16x8 v1 = ldsv(Vs + 32 * rs + lo[kk]);
;     o0 = mfma(v0, pf, o0);
;     o1 = mfma(v1, pf, o1);
;     ls = mfma16(ones, pf, ls);
;   }
.LBB0_278:
	s_or_b64 exec, exec, s[2:3]
	s_nop 7
	v_exp_f32_e32 v66, v66
	v_exp_f32_e32 v67, v67
	v_exp_f32_e32 v68, v68
	v_exp_f32_e32 v69, v69
	v_exp_f32_e32 v70, v70
	v_exp_f32_e32 v71, v71
	v_exp_f32_e32 v72, v72
	v_exp_f32_e32 v73, v73
	v_cvt_pk_bf16_f32 v66, v66, v67
	v_cvt_pk_bf16_f32 v67, v68, v69
	v_cvt_pk_bf16_f32 v68, v70, v71
	v_cvt_pk_bf16_f32 v69, v72, v73
	v_exp_f32_e32 v74, v74
	v_exp_f32_e32 v75, v75
	v_mfma_f32_32x32x16_bf16 v[50:65], v[98:101], v[66:69], v[50:65]
	v_exp_f32_e32 v76, v76
	v_exp_f32_e32 v77, v77
	v_exp_f32_e32 v78, v78
	v_exp_f32_e32 v79, v79
	v_exp_f32_e32 v80, v80
	v_exp_f32_e32 v81, v81
	v_cvt_pk_bf16_f32 v70, v74, v75
	v_mfma_f32_32x32x16_bf16 v[18:33], v[102:105], v[66:69], v[18:33]
	v_cvt_pk_bf16_f32 v71, v76, v77
	v_cvt_pk_bf16_f32 v73, v80, v81
	v_cvt_pk_bf16_f32 v72, v78, v79
	v_exp_f32_e32 v82, v82
	v_exp_f32_e32 v83, v83
	v_exp_f32_e32 v84, v84
	v_exp_f32_e32 v85, v85
	v_mfma_f32_32x32x16_bf16 v[50:65], v[106:109], v[70:73], v[50:65]
	v_exp_f32_e32 v86, v86
	v_exp_f32_e32 v87, v87
	v_exp_f32_e32 v88, v88
	v_exp_f32_e32 v89, v89
	v_exp_f32_e32 v90, v90
	v_exp_f32_e32 v91, v91
	v_exp_f32_e32 v92, v92
	v_mfma_f32_32x32x16_bf16 v[18:33], v[110:113], v[70:73], v[18:33]
	v_exp_f32_e32 v93, v93
	v_exp_f32_e32 v94, v94
	v_exp_f32_e32 v95, v95
	v_exp_f32_e32 v96, v96
	v_exp_f32_e32 v97, v97
	s_waitcnt vmcnt(0)
	s_addk_i32 s64, 0x2000
	v_mfma_f32_16x16x32_bf16 v[66:69], v[146:149], v[66:69], v[154:157]
	v_cmp_eq_u32_e32 vcc, s65, v180
	v_add_u32_e32 v207, 0x80, v207
	v_add_u32_e32 v208, -2, v208
	v_mfma_f32_16x16x32_bf16 v[66:69], v[146:149], v[70:73], v[66:69]
	v_cvt_pk_bf16_f32 v70, v82, v83
	v_cvt_pk_bf16_f32 v71, v84, v85
	v_cvt_pk_bf16_f32 v73, v88, v89
	v_cvt_pk_bf16_f32 v72, v86, v87
	s_nop 1
	v_mfma_f32_32x32x16_bf16 v[50:65], v[114:117], v[70:73], v[50:65]
	s_or_b64 s[40:41], vcc, s[40:41]
	s_mov_b64 s[42:43], -1
	s_barrier
	v_mfma_f32_32x32x16_bf16 v[18:33], v[118:121], v[70:73], v[18:33]
	v_mfma_f32_16x16x32_bf16 v[66:69], v[146:149], v[70:73], v[66:69]
	v_cvt_pk_bf16_f32 v70, v90, v91
	v_cvt_pk_bf16_f32 v71, v92, v93
	v_cvt_pk_bf16_f32 v73, v96, v97
	v_cvt_pk_bf16_f32 v72, v94, v95
	s_nop 1
	v_mfma_f32_32x32x16_bf16 v[50:65], v[122:125], v[70:73], v[50:65]
	v_mfma_f32_32x32x16_bf16 v[18:33], v[126:129], v[70:73], v[18:33]
	v_mfma_f32_16x16x32_bf16 v[154:157], v[146:149], v[70:73], v[66:69]
	s_andn2_b64 exec, exec, s[40:41]
	s_cbranch_execz .LBB0_291

; DI f32x16 mfma(bf16x8 a, bf16x8 b, f32x16 c) { return __builtin_amdgcn_mfma_f32_32x32x16_bf16(a, b, c, 0, 0, 0); }
; DI void diff_softmax_pv(const bf16x8 (&qf)[4], const u16* Ks, const u16* Vs, float& m, f32x4& ls0, f32x4& ls1, bf16x8 ones,
;                         f32x16 (&o)[2][2], float sl2, int dl, bool need_mask, bool first, int r, int h, int rs, const int (&lo)[4]) {
;     ...
;   const float nb = -sl2 * (float)dl - m;
; #pragma unroll
;   for (int i = 0; i < 16; ++i) {
;     const int ci = (i & 3) + 8 * (i >> 2);
;     b0[i] = fmaf(sl2, (float)ci, nb);
;     b1[i] = fmaf(sl2, (float)(ci + 32), nb);
;   }
;   {
;     __builtin_amdgcn_s_setprio(1);
;     f32x16 s0 = mfma(ldsv(Ks + lo[0]), qf[0], b0);
;     f32x16 s1 = mfma(ldsv(Ks + 32 * rs + lo[0]), qf[0], b1);
;     s0 = mfma(ldsv(Ks + lo[1]), qf[1], s0);
;     s1 = mfma(ldsv(Ks + 32 * rs + lo[1]), qf[1], s1);
;     __builtin_amdgcn_s_setprio(0);
;     if (need_mask) mask_causal(s0, s1, dl);
;     ...
;     f32x16 s0 = mfma(ldsv(Ks + lo[2]), qf[2], b0);
;     f32x16 s1 = mfma(ldsv(Ks + 32 * rs + lo[2]), qf[2], b1);
;     s0 = mfma(ldsv(Ks + lo[3]), qf[3], s0);
;     s1 = mfma(ldsv(Ks + 32 * rs + lo[3]), qf[3], s1);
.LBB0_281:
	s_or_b64 exec, exec, s[2:3]
	v_cvt_f32_i32_e32 v66, v207
	s_and_b32 s2, s64, 0x2000
	v_lshl_add_u32 v211, s2, 1, v176
	v_lshl_add_u32 v213, v183, 1, v211
	v_lshl_add_u32 v212, v184, 1, v211
	v_fma_f32 v229, -v178, v66, -v204
	v_lshl_add_u32 v246, v185, 1, v211
	v_lshl_add_u32 v247, v186, 1, v211
	ds_read_b128 v[114:117], v213
	ds_read_b128 v[214:217], v213 offset:4096
	ds_read_b128 v[218:221], v212
	ds_read_b128 v[222:225], v212 offset:4096
	ds_read_b128 v[230:233], v246
	ds_read_b128 v[234:237], v246 offset:4096
	ds_read_b128 v[238:241], v247
	ds_read_b128 v[242:245], v247 offset:4096
	v_cmp_eq_u32_e64 s[38:39], 0, v208
	v_fma_f32 v66, 0, v178, v229
	v_add_f32_e32 v67, v178, v229
	v_fmamk_f32 v68, v178, 0x40000000, v229
	v_fmamk_f32 v69, v178, 0x40400000, v229
	v_fmamk_f32 v70, v178, 0x41000000, v229
	v_fmamk_f32 v71, v178, 0x41100000, v229
	v_fmamk_f32 v72, v178, 0x41200000, v229
	v_fmamk_f32 v73, v178, 0x41300000, v229
	v_fmamk_f32 v74, v178, 0x41800000, v229
	v_fmamk_f32 v75, v178, 0x41880000, v229
	v_fmamk_f32 v76, v178, 0x41900000, v229
	v_fmamk_f32 v77, v178, 0x41980000, v229
	v_fmamk_f32 v78, v178, 0x41c00000, v229
	v_fmamk_f32 v79, v178, 0x41c80000, v229
	v_fmamk_f32 v80, v178, 0x41d00000, v229
	v_fmamk_f32 v81, v178, 0x41d80000, v229
	v_fmamk_f32 v82, v178, 0x42000000, v229
	v_fmamk_f32 v83, v178, 0x42040000, v229
	v_fmamk_f32 v84, v178, 0x42080000, v229
	v_fmamk_f32 v85, v178, 0x420c0000, v229
	v_fmamk_f32 v86, v178, 0x42200000, v229
	v_fmamk_f32 v87, v178, 0x42240000, v229
	v_fmamk_f32 v88, v178, 0x42280000, v229
	v_fmamk_f32 v89, v178, 0x422c0000, v229
	v_fmamk_f32 v90, v178, 0x42400000, v229
	v_fmamk_f32 v91, v178, 0x42440000, v229
	v_fmamk_f32 v92, v178, 0x42480000, v229
	v_fmamk_f32 v93, v178, 0x424c0000, v229
	v_fmamk_f32 v94, v178, 0x42600000, v229
	v_fmamk_f32 v95, v178, 0x42640000, v229
	v_fmamk_f32 v96, v178, 0x42680000, v229
	v_fmamk_f32 v97, v178, 0x426c0000, v229
	s_setprio 1
	s_waitcnt lgkmcnt(6)
	v_mfma_f32_32x32x16_bf16 v[98:113], v[114:117], v[130:133], v[66:81]
	v_mfma_f32_32x32x16_bf16 v[114:129], v[214:217], v[130:133], v[82:97]
	s_waitcnt lgkmcnt(5)
	v_mfma_f32_32x32x16_bf16 v[98:113], v[218:221], v[134:137], v[98:113]
	s_waitcnt lgkmcnt(4)
	v_mfma_f32_32x32x16_bf16 v[114:129], v[222:225], v[134:137], v[114:129]
	s_setprio 0
	s_and_saveexec_b64 s[2:3], s[38:39]
	s_cbranch_execz .LBB0_283
	v_cmp_lt_i32_e32 vcc, -1, v207
	s_nop 4
	v_cndmask_b32_e32 v98, v199, v98, vcc
	v_cmp_lt_i32_e32 vcc, 31, v207
	s_nop 1
	v_cndmask_b32_e32 v114, v199, v114, vcc
	v_cmp_lt_i32_e32 vcc, 0, v207
	s_nop 1
	v_cndmask_b32_e32 v99, v199, v99, vcc
	v_cmp_lt_i32_e32 vcc, 32, v207
	s_nop 1
	v_cndmask_b32_e32 v115, v199, v115, vcc
	v_cmp_lt_i32_e32 vcc, 1, v207
	s_nop 1
	v_cndmask_b32_e32 v100, v199, v100, vcc
	v_cmp_lt_i32_e32 vcc, 33, v207
	s_nop 1
	v_cndmask_b32_e32 v116, v199, v116, vcc
	v_cmp_lt_i32_e32 vcc, 2, v207
	s_nop 1
	v_cndmask_b32_e32 v101, v199, v101, vcc
	v_cmp_lt_i32_e32 vcc, 34, v207
	s_nop 1
	v_cndmask_b32_e32 v117, v199, v117, vcc
	v_cmp_lt_i32_e32 vcc, 7, v207
	s_nop 1
	v_cndmask_b32_e32 v102, v199, v102, vcc
	v_cmp_lt_i32_e32 vcc, 39, v207
	s_nop 1
	v_cndmask_b32_e32 v118, v199, v118, vcc
	v_cmp_lt_i32_e32 vcc, 8, v207
	s_nop 1
	v_cndmask_b32_e32 v103, v199, v103, vcc
	v_cmp_lt_i32_e32 vcc, 40, v207
	s_nop 1
	v_cndmask_b32_e32 v119, v199, v119, vcc
	v_cmp_lt_i32_e32 vcc, 9, v207
	s_nop 1
	v_cndmask_b32_e32 v104, v199, v104, vcc
	v_cmp_lt_i32_e32 vcc, 41, v207
	s_nop 1
	v_cndmask_b32_e32 v120, v199, v120, vcc
	v_cmp_lt_i32_e32 vcc, 10, v207
	s_nop 1
	v_cndmask_b32_e32 v105, v199, v105, vcc
	v_cmp_lt_i32_e32 vcc, 42, v207
	s_nop 1
	v_cndmask_b32_e32 v121, v199, v121, vcc
	v_cmp_lt_i32_e32 vcc, 15, v207
	s_nop 1
	v_cndmask_b32_e32 v106, v199, v106, vcc
	v_cmp_lt_i32_e32 vcc, 47, v207
	s_nop 1
	v_cndmask_b32_e32 v122, v199, v122, vcc
	v_cmp_lt_i32_e32 vcc, 16, v207
	s_nop 1
	v_cndmask_b32_e32 v107, v199, v107, vcc
	v_cmp_lt_i32_e32 vcc, 48, v207
	s_nop 1
	v_cndmask_b32_e32 v123, v199, v123, vcc
	v_cmp_lt_i32_e32 vcc, 17, v207
	s_nop 1
	v_cndmask_b32_e32 v108, v199, v108, vcc
	v_cmp_lt_i32_e32 vcc, 49, v207
	s_nop 1
	v_cndmask_b32_e32 v124, v199, v124, vcc
	v_cmp_lt_i32_e32 vcc, 18, v207
	s_nop 1
	v_cndmask_b32_e32 v109, v199, v109, vcc
	v_cmp_lt_i32_e32 vcc, 50, v207
	s_nop 1
	v_cndmask_b32_e32 v125, v199, v125, vcc
	v_cmp_lt_i32_e32 vcc, 23, v207
	s_nop 1
	v_cndmask_b32_e32 v110, v199, v110, vcc
	v_cmp_lt_i32_e32 vcc, 55, v207
	s_nop 1
	v_cndmask_b32_e32 v126, v199, v126, vcc
	v_cmp_lt_i32_e32 vcc, 24, v207
	s_nop 1
	v_cndmask_b32_e32 v111, v199, v111, vcc
	v_cmp_lt_i32_e32 vcc, 56, v207
	s_nop 1
	v_cndmask_b32_e32 v127, v199, v127, vcc
	v_cmp_lt_i32_e32 vcc, 25, v207
	s_nop 1
	v_cndmask_b32_e32 v112, v199, v112, vcc
	v_cmp_lt_i32_e32 vcc, 57, v207
	s_nop 1
	v_cndmask_b32_e32 v128, v199, v128, vcc
	v_cmp_lt_i32_e32 vcc, 26, v207
	s_nop 1
	v_cndmask_b32_e32 v113, v199, v113, vcc
	v_cmp_lt_i32_e32 vcc, 58, v207
	s_nop 1
	v_cndmask_b32_e32 v129, v199, v129, vcc

; DI float ex2(float x) { return __builtin_amdgcn_exp2f(x); }
; DI f32x16 mfma(bf16x8 a, bf16x8 b, f32x16 c) { return __builtin_amdgcn_mfma_f32_32x32x16_bf16(a, b, c, 0, 0, 0); }
; DI f32x4 mfma16(bf16x8 a, bf16x8 b, f32x4 c) { return __builtin_amdgcn_mfma_f32_16x16x32_bf16(a, b, c, 0, 0, 0); }
; DI void pv_frag_step(f32x16& s0, f32x16& s1, const u16* Vs, f32x16& o0, f32x16& o1, f32x4& ls, bf16x8 ones, int rs, const int (&lo)[4]) {
; #pragma unroll
;   for (int i = 0; i < 16; ++i) { s0[i] = ex2(s0[i]); s1[i] = ex2(s1[i]); }
; #pragma unroll
;   for (int kk = 0; kk < 4; ++kk) {
;     const int s = kk & 1;
;     unsigned u0, u1, u2, u3;
;     if (kk < 2) {
;       u0 = pk2(s0[8 * s], s0[8 * s + 1]); u1 = pk2(s0[8 * s + 2], s0[8 * s + 3]);
;       u2 = pk2(s0[8 * s + 4], s0[8 * s + 5]); u3 = pk2(s0[8 * s + 6], s0[8 * s + 7]);
;     } else {
;       u0 = pk2(s1[8 * s], s1[8 * s + 1]); u1 = pk2(s1[8 * s + 2], s1[8 * s + 3]);
;       u2 = pk2(s1[8 * s + 4], s1[8 * s + 5]); u3 = pk2(s1[8 * s + 6], s1[8 * s + 7]);
;     }
;     u32x4 uu = {u0, u1, u2, u3};
;     bf16x8 pf = __builtin_bit_cast(bf16x8, uu);
;     bf16x8 v0 = ldsv(Vs + lo[kk]);
;     bf16x8 v1 = ldsv(Vs + 32 * rs + lo[kk]);
;     o0 = mfma(v0, pf, o0);
;     o1 = mfma(v1, pf, o1);
;     ls = mfma16(ones, pf, ls);
;   }
; DI void diff_softmax_pv(const bf16x8 (&qf)[4], const u16* Ks, const u16* Vs, float& m, f32x4& ls0, f32x4& ls1, bf16x8 ones,
;                         f32x16 (&o)[2][2], float sl2, int dl, bool need_mask, bool first, int r, int h, int rs, const int (&lo)[4]) {
;     ...
;     f32x16 s0 = mfma(ldsv(Ks + lo[2]), qf[2], b0);
;     f32x16 s1 = mfma(ldsv(Ks + 32 * rs + lo[2]), qf[2], b1);
;     s0 = mfma(ldsv(Ks + lo[3]), qf[3], s0);
;     s1 = mfma(ldsv(Ks + 32 * rs + lo[3]), qf[3], s1);
;     if (need_mask) mask_causal(s0, s1, dl);
.LBB0_289:
	v_exp_f32_e32 v98, v98
	v_exp_f32_e32 v99, v99
	v_exp_f32_e32 v100, v100
	v_exp_f32_e32 v101, v101
	v_exp_f32_e32 v102, v102
	v_exp_f32_e32 v103, v103
	v_exp_f32_e32 v104, v104
	v_exp_f32_e32 v105, v105
	v_exp_f32_e32 v218, v118
	v_exp_f32_e32 v219, v119
	v_exp_f32_e32 v220, v120
	v_exp_f32_e32 v221, v121
	v_exp_f32_e32 v118, v106
	v_exp_f32_e32 v119, v107
	v_exp_f32_e32 v120, v108
	v_exp_f32_e32 v121, v109
	v_cvt_pk_bf16_f32 v106, v98, v99
	v_cvt_pk_bf16_f32 v107, v100, v101
	v_cvt_pk_bf16_f32 v109, v104, v105
	v_cvt_pk_bf16_f32 v108, v102, v103
	ds_read_b128 v[98:101], v213 offset:8192
	ds_read_b128 v[102:105], v213 offset:12288
	v_exp_f32_e32 v110, v110
	v_exp_f32_e32 v111, v111
	v_exp_f32_e32 v112, v112
	v_exp_f32_e32 v113, v113
	s_waitcnt lgkmcnt(1)
	v_mfma_f32_32x32x16_bf16 v[2:17], v[98:101], v[106:109], v[2:17]
	v_exp_f32_e32 v214, v114
	v_exp_f32_e32 v215, v115
	v_exp_f32_e32 v216, v116
	v_exp_f32_e32 v217, v117
	v_cvt_pk_bf16_f32 v118, v118, v119
	v_cvt_pk_bf16_f32 v119, v120, v121
	v_cvt_pk_bf16_f32 v121, v112, v113
	s_waitcnt lgkmcnt(0)
	v_mfma_f32_32x32x16_bf16 v[34:49], v[102:105], v[106:109], v[34:49]
	v_cvt_pk_bf16_f32 v120, v110, v111
	v_exp_f32_e32 v227, v127
	v_cvt_pk_bf16_f32 v127, v216, v217
	v_lshl_add_u32 v216, v185, 1, v211
	v_exp_f32_e32 v222, v122
	v_exp_f32_e32 v223, v123
	v_exp_f32_e32 v224, v124
	v_mfma_f32_16x16x32_bf16 v[114:117], v[146:149], v[106:109], v[150:153]
	ds_read_b128 v[106:109], v212 offset:8192
	ds_read_b128 v[110:113], v212 offset:12288
	v_exp_f32_e32 v225, v125
	v_exp_f32_e32 v226, v126
	s_waitcnt lgkmcnt(1)
	v_mfma_f32_32x32x16_bf16 v[2:17], v[106:109], v[118:121], v[2:17]
	v_exp_f32_e32 v228, v128
	v_exp_f32_e32 v229, v129
	v_cvt_pk_bf16_f32 v126, v214, v215
	v_cvt_pk_bf16_f32 v129, v220, v221
	v_cvt_pk_bf16_f32 v128, v218, v219
	v_lshl_add_u32 v211, v186, 1, v211
	v_cvt_pk_bf16_f32 v212, v222, v223
	s_waitcnt lgkmcnt(0)
	v_mfma_f32_32x32x16_bf16 v[34:49], v[110:113], v[118:121], v[34:49]
	v_cvt_pk_bf16_f32 v213, v224, v225
	v_cvt_pk_bf16_f32 v215, v228, v229
	v_cvt_pk_bf16_f32 v214, v226, v227
	v_mfma_f32_16x16x32_bf16 v[122:125], v[146:149], v[118:121], v[114:117]
	s_nop 2
	ds_read_b128 v[114:117], v216 offset:8192
	ds_read_b128 v[118:121], v216 offset:12288
	s_waitcnt lgkmcnt(1)
	v_mfma_f32_32x32x16_bf16 v[2:17], v[114:117], v[126:129], v[2:17]
	s_waitcnt lgkmcnt(0)
	v_mfma_f32_32x32x16_bf16 v[34:49], v[118:121], v[126:129], v[34:49]
	v_mfma_f32_16x16x32_bf16 v[150:153], v[146:149], v[126:129], v[122:125]
	s_nop 2
	ds_read_b128 v[122:125], v211 offset:8192
	ds_read_b128 v[126:129], v211 offset:12288
	s_waitcnt lgkmcnt(1)
	v_mfma_f32_32x32x16_bf16 v[2:17], v[122:125], v[212:215], v[2:17]
	s_waitcnt lgkmcnt(0)
	v_mfma_f32_32x32x16_bf16 v[34:49], v[126:129], v[212:215], v[34:49]
	v_mfma_f32_16x16x32_bf16 v[150:153], v[146:149], v[212:215], v[150:153]
	v_mfma_f32_32x32x16_bf16 v[66:81], v[230:233], v[138:141], v[66:81]
	v_mfma_f32_32x32x16_bf16 v[82:97], v[234:237], v[138:141], v[82:97]
	v_mfma_f32_32x32x16_bf16 v[66:81], v[238:241], v[142:145], v[66:81]
	v_mfma_f32_32x32x16_bf16 v[82:97], v[242:245], v[142:145], v[82:97]
	s_and_saveexec_b64 s[2:3], s[38:39]
	s_cbranch_execz .LBB0_278
	v_cmp_lt_i32_e32 vcc, -1, v207
	s_nop 7
	v_cndmask_b32_e32 v66, v199, v66, vcc
	v_cmp_lt_i32_e32 vcc, 31, v207
	s_nop 1
	v_cndmask_b32_e32 v82, v199, v82, vcc
	v_cmp_lt_i32_e32 vcc, 0, v207
	s_nop 1
	v_cndmask_b32_e32 v67, v199, v67, vcc
	v_cmp_lt_i32_e32 vcc, 32, v207
	s_nop 1
	v_cndmask_b32_e32 v83, v199, v83, vcc
	v_cmp_lt_i32_e32 vcc, 1, v207
	s_nop 1
	v_cndmask_b32_e32 v68, v199, v68, vcc
	v_cmp_lt_i32_e32 vcc, 33, v207
	s_nop 1
	v_cndmask_b32_e32 v84, v199, v84, vcc
	v_cmp_lt_i32_e32 vcc, 2, v207
	s_nop 1
	v_cndmask_b32_e32 v69, v199, v69, vcc
	v_cmp_lt_i32_e32 vcc, 34, v207
	s_nop 1
	v_cndmask_b32_e32 v85, v199, v85, vcc
	v_cmp_lt_i32_e32 vcc, 7, v207
	s_nop 1
	v_cndmask_b32_e32 v70, v199, v70, vcc
	v_cmp_lt_i32_e32 vcc, 39, v207
	s_nop 1
	v_cndmask_b32_e32 v86, v199, v86, vcc
	v_cmp_lt_i32_e32 vcc, 8, v207
	s_nop 1
	v_cndmask_b32_e32 v71, v199, v71, vcc
	v_cmp_lt_i32_e32 vcc, 40, v207
	s_nop 1
	v_cndmask_b32_e32 v87, v199, v87, vcc
	v_cmp_lt_i32_e32 vcc, 9, v207
	s_nop 1
	v_cndmask_b32_e32 v72, v199, v72, vcc
	v_cmp_lt_i32_e32 vcc, 41, v207
	s_nop 1
	v_cndmask_b32_e32 v88, v199, v88, vcc
	v_cmp_lt_i32_e32 vcc, 10, v207
	s_nop 1
	v_cndmask_b32_e32 v73, v199, v73, vcc
	v_cmp_lt_i32_e32 vcc, 42, v207
	s_nop 1
	v_cndmask_b32_e32 v89, v199, v89, vcc
	v_cmp_lt_i32_e32 vcc, 15, v207
	s_nop 1
	v_cndmask_b32_e32 v74, v199, v74, vcc
	v_cmp_lt_i32_e32 vcc, 47, v207
	s_nop 1
	v_cndmask_b32_e32 v90, v199, v90, vcc
	v_cmp_lt_i32_e32 vcc, 16, v207
	s_nop 1
	v_cndmask_b32_e32 v75, v199, v75, vcc
	v_cmp_lt_i32_e32 vcc, 48, v207
	s_nop 1
	v_cndmask_b32_e32 v91, v199, v91, vcc
	v_cmp_lt_i32_e32 vcc, 17, v207
	s_nop 1
	v_cndmask_b32_e32 v76, v199, v76, vcc
	v_cmp_lt_i32_e32 vcc, 49, v207
	s_nop 1
	v_cndmask_b32_e32 v92, v199, v92, vcc
	v_cmp_lt_i32_e32 vcc, 18, v207
	s_nop 1
	v_cndmask_b32_e32 v77, v199, v77, vcc
	v_cmp_lt_i32_e32 vcc, 50, v207
	s_nop 1
	v_cndmask_b32_e32 v93, v199, v93, vcc
	v_cmp_lt_i32_e32 vcc, 23, v207
	s_nop 1
	v_cndmask_b32_e32 v78, v199, v78, vcc
	v_cmp_lt_i32_e32 vcc, 55, v207
	s_nop 1
	v_cndmask_b32_e32 v94, v199, v94, vcc
	v_cmp_lt_i32_e32 vcc, 24, v207
	s_nop 1
	v_cndmask_b32_e32 v79, v199, v79, vcc
	v_cmp_lt_i32_e32 vcc, 56, v207
	s_nop 1
	v_cndmask_b32_e32 v95, v199, v95, vcc
	v_cmp_lt_i32_e32 vcc, 25, v207
	s_nop 1
	v_cndmask_b32_e32 v80, v199, v80, vcc
	v_cmp_lt_i32_e32 vcc, 57, v207
	s_nop 1
	v_cndmask_b32_e32 v96, v199, v96, vcc
	v_cmp_lt_i32_e32 vcc, 26, v207
	s_nop 1
	v_cndmask_b32_e32 v81, v199, v81, vcc
	v_cmp_lt_i32_e32 vcc, 58, v207
	s_nop 1
	v_cndmask_b32_e32 v97, v199, v97, vcc
	s_branch .LBB0_278

; __global__ void __launch_bounds__(256, 2) hymba_mega(Params p) {
;   cg::grid_group grid = cg::this_grid();
;   __shared__ __attribute__((aligned(16))) u16 sm[SMEM_U16];
;   __shared__ int s_item;
;   __shared__ int s_done[4];
;   const int wv = __builtin_amdgcn_readfirstlane((int)threadIdx.x >> 6);
	.amdhsa_kernel _Z10hymba_mega6Params
		.amdhsa_group_segment_fixed_size 73764
		.amdhsa_private_segment_fixed_size 0
		.amdhsa_kernarg_size 440
		.amdhsa_user_sgpr_count 2
		.amdhsa_user_sgpr_dispatch_ptr 0
		.amdhsa_user_sgpr_queue_ptr 0
		.amdhsa_user_sgpr_kernarg_segment_ptr 1
		.amdhsa_user_sgpr_dispatch_id 0
		.amdhsa_user_sgpr_kernarg_preload_length 0
		.amdhsa_user_sgpr_kernarg_preload_offset 0
		.amdhsa_user_sgpr_private_segment_size 0
		.amdhsa_uses_dynamic_stack 0
		.amdhsa_enable_private_segment 0
		.amdhsa_system_sgpr_workgroup_id_x 1
		.amdhsa_system_sgpr_workgroup_id_y 0
		.amdhsa_system_sgpr_workgroup_id_z 0
		.amdhsa_system_sgpr_workgroup_info 0
		.amdhsa_system_vgpr_workitem_id 2
		.amdhsa_next_free_vgpr 256
		.amdhsa_next_free_sgpr 102
		.amdhsa_accum_offset 256
		.amdhsa_reserve_vcc 1
		.amdhsa_float_round_mode_32 0
		.amdhsa_float_round_mode_16_64 0
		.amdhsa_float_denorm_mode_32 3
		.amdhsa_float_denorm_mode_16_64 3
		.amdhsa_dx10_clamp 1
		.amdhsa_ieee_mode 1
		.amdhsa_fp16_overflow 0
		.amdhsa_tg_split 0
		.amdhsa_exception_fp_ieee_invalid_op 0
		.amdhsa_exception_fp_denorm_src 0
		.amdhsa_exception_fp_ieee_div_zero 0
		.amdhsa_exception_fp_ieee_overflow 0
		.amdhsa_exception_fp_ieee_underflow 0
		.amdhsa_exception_fp_ieee_inexact 0
		.amdhsa_exception_int_div_zero 0
	.end_amdhsa_kernel

; __global__ void __launch_bounds__(256, 2) hymba_mega(Params p) {
;   cg::grid_group grid = cg::this_grid();
;   __shared__ __attribute__((aligned(16))) u16 sm[SMEM_U16];
;   __shared__ int s_item;
;   __shared__ int s_done[4];
;   const int wv = __builtin_amdgcn_readfirstlane((int)threadIdx.x >> 6);
amdhsa.kernels:
  - .agpr_count:     0
    .args:
      - .offset:         0
        .size:           184
        .value_kind:     by_value
      - .offset:         184
        .size:           4
        .value_kind:     hidden_block_count_x
      - .offset:         188
        .size:           4
        .value_kind:     hidden_block_count_y
      - .offset:         192
        .size:           4
        .value_kind:     hidden_block_count_z
      - .offset:         196
        .size:           2
        .value_kind:     hidden_group_size_x
      - .offset:         198
        .size:           2
        .value_kind:     hidden_group_size_y
      - .offset:         200
        .size:           2
        .value_kind:     hidden_group_size_z
      - .offset:         202
        .size:           2
        .value_kind:     hidden_remainder_x
      - .offset:         204
        .size:           2
        .value_kind:     hidden_remainder_y
      - .offset:         206
        .size:           2
        .value_kind:     hidden_remainder_z
      - .offset:         224
        .size:           8
        .value_kind:     hidden_global_offset_x
      - .offset:         232
        .size:           8
        .value_kind:     hidden_global_offset_y
      - .offset:         240
        .size:           8
        .value_kind:     hidden_global_offset_z
      - .offset:         248
        .size:           2
        .value_kind:     hidden_grid_dims
      - .offset:         272
        .size:           8
        .value_kind:     hidden_multigrid_sync_arg
    .group_segment_fixed_size: 73764
    .kernarg_segment_align: 8
    .kernarg_segment_size: 440
    .language:       OpenCL C
    .language_version:
      - 2
      - 0
    .max_flat_workgroup_size: 256
    .name:           _Z10hymba_mega6Params
    .private_segment_fixed_size: 0
    .sgpr_count:     108
    .sgpr_spill_count: 103
    .symbol:         _Z10hymba_mega6Params.kd
    .uniform_work_group_size: 1
    .uses_dynamic_stack: false
    .vgpr_count:     256
    .vgpr_spill_count: 0
    .wavefront_size: 64
